# v108 + P12 LN gamma/beta in registers
# baseline (speedup 1.0000x reference)
.LBB0_1702:
	s_andn2_b64 vcc, exec, s[4:5]
	s_cbranch_vccnz .LBB0_1715
	s_mov_b64 s[6:7], s[0:1]
	s_mov_b64 s[8:9], s[0:1]
	s_mov_b64 s[4:5], s[0:1]
	s_mov_b64 s[12:13], s[0:1]
	s_mov_b64 s[14:15], s[0:1]
	v_mov_b32_e32 v0, v190
	s_nop 0
	v_readfirstlane_b32 s10, v0
	s_ashr_i32 s18, s10, 6
	s_mov_b32 s10, s2
	s_lshl_b32 s19, s10, 3
	s_add_i32 s10, s19, s18
	s_cmpk_gt_i32 s10, 0x3fff
	s_cbranch_scc1 .LBB0_1710
	s_load_dwordx2 s[6:7], s[6:7], 0xe0
	s_ashr_i32 s11, s10, 31
	s_lshl_b64 s[22:23], s[10:11], 12
	s_waitcnt vmcnt(0)
	v_and_b32_e32 v6, 63, v0
	v_lshlrev_b32_e32 v0, 4, v6
	s_waitcnt lgkmcnt(0)
	s_add_u32 s26, s6, s22
	s_addc_u32 s27, s7, s23
	v_lshl_add_u64 v[2:3], s[26:27], 0, v[0:1]
	s_mov_b64 s[26:27], 0x20100000
	v_lshl_add_u64 v[4:5], v[2:3], 0, s[26:27]
	s_mov_b32 s26, 0x20100000
	v_add_co_u32_e32 v2, vcc, s26, v2
	global_load_dwordx4 v[26:29], v[4:5], off offset:1024
	global_load_dwordx4 v[18:21], v[4:5], off offset:2048
	v_addc_co_u32_e32 v3, vcc, 0, v3, vcc
	global_load_dwordx4 v[22:25], v[4:5], off offset:3072
	global_load_dwordx4 v[30:33], v[2:3], off
	s_load_dwordx2 s[26:27], s[8:9], 0xc8
	s_nop 0
	s_load_dwordx2 s[4:5], s[4:5], 0xd0
	s_nop 0
	s_load_dwordx2 s[36:37], s[12:13], 0xe0
	s_nop 0
	s_load_dwordx2 s[14:15], s[14:15], 0xe0
	v_and_b32_e32 v2, 64, v197
	v_xor_b32_e32 v4, 16, v197
	v_add_u32_e32 v10, 64, v2
	v_xor_b32_e32 v8, 32, v197
	v_cmp_lt_i32_e64 s[8:9], v4, v10
	v_lshlrev_b32_e32 v2, 5, v6
	v_mov_b32_e32 v3, v1
	v_cndmask_b32_e64 v11, v197, v4, s[8:9]
	v_cmp_lt_i32_e64 s[8:9], v8, v10
	v_mov_b32_e32 v5, v1
	v_mov_b32_e32 v7, v1
	v_mov_b32_e32 v9, v1
	v_cmp_eq_u32_e32 vcc, 0, v6
	v_cndmask_b32_e64 v10, v197, v8, s[8:9]
	v_or_b32_e32 v4, 0x800, v2
	v_or_b32_e32 v6, 0x1000, v2
	v_or_b32_e32 v8, 0x1800, v2
	s_waitcnt lgkmcnt(0)
	s_cmp_lg_u64 s[14:15], 0
	v_lshl_add_u64 v[36:37], s[4:5], 0, v[2:3]
	v_lshl_add_u64 v[40:41], s[4:5], 0, v[4:5]
	v_lshl_add_u64 v[44:45], s[4:5], 0, v[6:7]
	v_lshl_add_u64 v[48:49], s[4:5], 0, v[8:9]
	s_cselect_b64 s[4:5], -1, 0
	s_lshl_b64 s[8:9], s[10:11], 3
	s_and_b64 s[12:13], s[4:5], vcc
	s_add_u32 s14, s14, s8
	s_addc_u32 s15, s15, s9
	s_add_u32 s64, s36, s22
	s_addc_u32 s65, s37, s23
	s_add_i32 s4, s20, s18
	s_add_i32 s4, s4, s19
	s_ashr_i32 s5, s4, 31
	s_lshl_b64 s[4:5], s[4:5], 12
	v_lshlrev_b32_e32 v68, 2, v11
	v_lshlrev_b32_e32 v69, 2, v10
	v_lshl_add_u64 v[34:35], s[26:27], 0, v[2:3]
	v_lshl_add_u64 v[38:39], s[26:27], 0, v[4:5]
	v_lshl_add_u64 v[42:43], s[26:27], 0, v[6:7]
	v_lshl_add_u64 v[46:47], s[26:27], 0, v[8:9]
	global_load_dwordx4 v[88:91], v[34:35], off
	global_load_dwordx4 v[92:95], v[34:35], off offset:16
	global_load_dwordx4 v[96:99], v[36:37], off
	global_load_dwordx4 v[100:103], v[36:37], off offset:16
	global_load_dwordx4 v[104:107], v[38:39], off
	global_load_dwordx4 v[108:111], v[38:39], off offset:16
	global_load_dwordx4 v[130:133], v[40:41], off
	global_load_dwordx4 v[134:137], v[40:41], off offset:16
	global_load_dwordx4 v[138:141], v[42:43], off
	global_load_dwordx4 v[142:145], v[42:43], off offset:16
	global_load_dwordx4 v[158:161], v[44:45], off
	global_load_dwordx4 v[162:165], v[44:45], off offset:16
	global_load_dwordx4 v[166:169], v[46:47], off
	global_load_dwordx4 v[170:173], v[46:47], off offset:16
	global_load_dwordx4 v[176:179], v[48:49], off
	global_load_dwordx4 v[180:183], v[48:49], off offset:16
	s_add_u32 s68, s6, s4
	s_addc_u32 s69, s7, s5
	s_waitcnt vmcnt(0)
	v_mov_b64_e32 v[6:7], v[26:27]
	s_waitcnt vmcnt(2)
	v_mov_b64_e32 v[2:3], v[18:19]
	v_mov_b64_e32 v[4:5], v[20:21]
	s_waitcnt vmcnt(1)
	v_mov_b64_e32 v[14:15], v[22:23]
	s_waitcnt vmcnt(0)
	v_mov_b64_e32 v[10:11], v[30:31]
	v_mov_b64_e32 v[8:9], v[28:29]
	v_mov_b64_e32 v[16:17], v[24:25]
	v_mov_b64_e32 v[12:13], v[32:33]
	s_branch .LBB0_1706
.LBB0_1705:
	s_or_b64 exec, exec, s[4:5]
	v_pk_mul_f32 v[66:67], v[66:67], v[24:25] op_sel_hi:[1,0]
	v_pk_mul_f32 v[64:65], v[64:65], v[24:25] op_sel_hi:[1,0]
	v_pk_mul_f32 v[62:63], v[62:63], v[24:25] op_sel_hi:[1,0]
	v_pk_mul_f32 v[86:87], v[60:61], v[24:25] op_sel_hi:[1,0]
	v_lshl_add_u64 v[60:61], s[64:65], 0, v[0:1]
	v_add_co_u32_e32 v60, vcc, s85, v60
	v_pk_mul_f32 v[58:59], v[58:59], v[24:25] op_sel_hi:[1,0]
	s_nop 0
	v_addc_co_u32_e32 v61, vcc, 0, v61, vcc
	v_pk_mul_f32 v[56:57], v[56:57], v[24:25] op_sel_hi:[1,0]
	v_pk_mul_f32 v[54:55], v[54:55], v[24:25] op_sel_hi:[1,0]
	v_pk_mul_f32 v[52:53], v[52:53], v[24:25] op_sel_hi:[1,0]
	v_pk_mul_f32 v[50:51], v[50:51], v[24:25] op_sel_hi:[1,0]
	v_pk_mul_f32 v[32:33], v[32:33], v[24:25] op_sel_hi:[1,0]
	v_pk_mul_f32 v[30:31], v[30:31], v[24:25] op_sel_hi:[1,0]
	v_pk_mul_f32 v[28:29], v[28:29], v[24:25] op_sel_hi:[1,0]
	s_add_u32 s14, s14, s56
	s_addc_u32 s15, s15, s57
	s_add_u32 s64, s64, s58
	s_addc_u32 s65, s65, s59
	s_add_u32 s68, s68, s58
	s_addc_u32 s69, s69, s59
	s_andn2_b64 vcc, exec, s[72:73]
	v_pk_fma_f32 v[66:67], v[66:67], v[90:91], v[98:99]
	v_pk_fma_f32 v[64:65], v[64:65], v[88:89], v[96:97]
	v_pk_fma_f32 v[70:71], v[62:63], v[94:95], v[102:103]
	v_pk_fma_f32 v[72:73], v[86:87], v[92:93], v[100:101]
	v_cvt_pk_bf16_f32 v62, v64, v65
	v_cvt_pk_bf16_f32 v63, v66, v67
	v_cvt_pk_bf16_f32 v64, v72, v73
	v_cvt_pk_bf16_f32 v65, v70, v71
	global_store_dwordx4 v[60:61], v[62:65], off
	s_nop 1
	s_nop 0
	v_pk_mul_f32 v[66:67], v[26:27], v[24:25] op_sel_hi:[1,0]
	v_pk_fma_f32 v[58:59], v[58:59], v[106:107], v[132:133]
	v_pk_fma_f32 v[56:57], v[56:57], v[104:105], v[130:131]
	v_pk_fma_f32 v[62:63], v[54:55], v[110:111], v[136:137]
	v_pk_fma_f32 v[54:55], v[52:53], v[108:109], v[134:135]
	v_cvt_pk_bf16_f32 v52, v56, v57
	v_cvt_pk_bf16_f32 v53, v58, v59
	v_cvt_pk_bf16_f32 v54, v54, v55
	v_cvt_pk_bf16_f32 v55, v62, v63
	global_store_dwordx4 v[60:61], v[52:55], off offset:1024
	s_nop 1
	s_nop 0
	v_pk_fma_f32 v[50:51], v[50:51], v[140:141], v[160:161]
	v_pk_fma_f32 v[32:33], v[32:33], v[138:139], v[158:159]
	v_pk_fma_f32 v[52:53], v[30:31], v[144:145], v[164:165]
	v_pk_fma_f32 v[30:31], v[28:29], v[142:143], v[162:163]
	v_cvt_pk_bf16_f32 v28, v32, v33
	v_cvt_pk_bf16_f32 v29, v50, v51
	v_cvt_pk_bf16_f32 v30, v30, v31
	v_cvt_pk_bf16_f32 v31, v52, v53
	global_store_dwordx4 v[60:61], v[28:31], off offset:2048
	s_nop 1
	s_nop 0
	v_pk_mul_f32 v[58:59], v[22:23], v[24:25] op_sel_hi:[1,0]
	v_pk_mul_f32 v[70:71], v[20:21], v[24:25] op_sel_hi:[1,0]
	v_pk_mul_f32 v[72:73], v[18:19], v[24:25] op_sel_hi:[1,0]
	s_waitcnt vmcnt(3)
	v_mov_b64_e32 v[24:25], v[16:17]
	v_mov_b64_e32 v[20:21], v[4:5]
	v_mov_b64_e32 v[28:29], v[8:9]
	v_mov_b64_e32 v[22:23], v[14:15]
	v_mov_b64_e32 v[18:19], v[2:3]
	v_mov_b64_e32 v[26:27], v[6:7]
	v_pk_fma_f32 v[32:33], v[58:59], v[168:169], v[178:179]
	v_pk_fma_f32 v[30:31], v[66:67], v[166:167], v[176:177]
	v_pk_fma_f32 v[50:51], v[70:71], v[172:173], v[182:183]
	v_pk_fma_f32 v[52:53], v[72:73], v[170:171], v[180:181]
	v_cvt_pk_bf16_f32 v30, v30, v31
	v_cvt_pk_bf16_f32 v31, v32, v33
	v_cvt_pk_bf16_f32 v32, v52, v53
	v_cvt_pk_bf16_f32 v33, v50, v51
	global_store_dwordx4 v[60:61], v[30:33], off offset:3072
	s_nop 1
	s_nop 1
	v_mov_b64_e32 v[32:33], v[12:13]
	v_mov_b64_e32 v[30:31], v[10:11]
	s_cbranch_vccz .LBB0_1710
